# adds G==256 guard on the gMLP rebalance and a batched layer-0 input-norm phase (gain loaded once, four rows in flight, next batch prefetched)
# speedup vs baseline: 1.0051x; 1.0051x over previous
.LBB0_153:
	s_or_b64 exec, exec, s[14:15]
	v_mov_b32_e32 v0, v220
	s_waitcnt lgkmcnt(0)
	s_barrier
	v_readlane_b32 s1, v254, 7
	v_readfirstlane_b32 s0, v0
	s_ashr_i32 s0, s0, 6
	s_add_i32 s0, s0, s1
	v_readlane_b32 s4, v254, 0
	v_readlane_b32 s5, v254, 1
	s_cmpk_gt_i32 s0, 0x41ff
	s_cbranch_scc1 .LBB0_160
	v_mov_b32_e32 v1, 0x70000
	s_nop 1
	global_load_dwordx2 v[2:3], v1, s[4:5] offset:16
	global_load_dwordx2 v[4:5], v1, s[4:5] offset:48
	global_load_dwordx2 v[6:7], v1, s[4:5]
	s_ashr_i32 s1, s0, 31
	v_and_b32_e32 v0, 63, v0
	v_mov_b32_e32 v9, 0
	s_ashr_i32 s51, s50, 31
	s_lshl_b64 s[10:11], s[0:1], 11
	v_lshlrev_b32_e32 v10, 3, v0
	v_mov_b32_e32 v11, v9
	s_add_u32 s16, s4, s10
	s_mov_b64 s[8:9], 0xe000000
	v_lshlrev_b32_e32 v8, 4, v0
	v_or_b32_e32 v12, 64, v0
	v_or_b32_e32 v14, 0x80, v0
	v_or_b32_e32 v26, 0xc0, v0
	v_lshlrev_b32_e32 v38, 4, v0
	v_lshl_add_u64 v[0:1], s[4:5], 0, v[10:11]
	s_addc_u32 s17, s5, s11
	s_mov_b64 s[12:13], 0x11880600
	s_waitcnt vmcnt(0)
	v_lshl_add_u64 v[16:17], v[0:1], 0, s[8:9]
	s_lshl_b64 s[20:21], s[0:1], 12
	v_lshl_add_u64 v[0:1], s[16:17], 0, v[10:11]
	v_lshl_add_u64 v[18:19], v[0:1], 0, s[12:13]
	s_mov_b64 s[14:15], 0x800
	s_mov_b32 s7, 0
	s_movk_i32 s18, 0x1800
	v_mbcnt_hi_u32_b32 v36, -1, v91
	v_mov_b32_e32 v37, 0x358637bd
	s_mov_b32 s19, 0x800000
	v_lshlrev_b32_e32 v39, 4, v12
	v_lshlrev_b32_e32 v40, 4, v14
	s_lshl_b64 s[8:9], s[50:51], 11
	s_lshl_b64 s[10:11], s[50:51], 12
	v_lshlrev_b32_e32 v41, 4, v26
	v_lshl_add_u64 v[20:21], v[2:3], 0, v[8:9]
	v_lshl_add_u64 v[22:23], v[4:5], 0, v[8:9]
	v_lshl_add_u64 v[0:1], v[6:7], 0, s[20:21]
	v_lshl_add_u64 v[0:1], v[0:1], 0, v[8:9]
	v_lshl_add_u64 v[24:25], v[0:1], 0, s[14:15]
	s_cmpk_lg_i32 s42, 0x100
	s_cbranch_scc1 .LBB0_156
	v_xor_b32_e32 v212, 1, v36
	v_xor_b32_e32 v213, 2, v36
	v_xor_b32_e32 v214, 4, v36
	v_xor_b32_e32 v215, 8, v36
	v_xor_b32_e32 v216, 16, v36
	v_xor_b32_e32 v217, 32, v36
	v_lshlrev_b32_e32 v212, 2, v212
	v_lshlrev_b32_e32 v213, 2, v213
	v_lshlrev_b32_e32 v214, 2, v214
	v_lshlrev_b32_e32 v215, 2, v215
	v_lshlrev_b32_e32 v216, 2, v216
	v_lshlrev_b32_e32 v217, 2, v217
	global_load_dwordx4 v[92:95], v[22:23], off
	global_load_dwordx4 v[96:99], v[22:23], off offset:1024
	global_load_dwordx4 v[100:103], v[22:23], off offset:2048
	global_load_dwordx4 v[104:107], v[22:23], off offset:3072
	s_mov_b32 s16, 0xfffff800
	s_mov_b32 s17, -1
	v_lshl_add_u64 v[84:85], v[24:25], 0, s[16:17]
	s_mov_b32 s16, 0xfffffa00
	v_lshl_add_u64 v[86:87], v[18:19], 0, s[16:17]
	s_lshl_b32 s16, s0, 11
	s_mov_b32 s17, 0
	v_lshl_add_u64 v[16:17], v[16:17], 0, s[16:17]
	s_add_u32 s12, s4, 0x0
	s_addc_u32 s13, s5, 0
	s_add_u32 s14, s12, 0x1000
	s_addc_u32 s15, s13, 0
	global_load_dwordx4 v[108:111], v38, s[12:13]
	global_load_dwordx4 v[124:127], v38, s[14:15]
	global_load_dwordx4 v[112:115], v38, s[12:13] offset:1024
	global_load_dwordx4 v[128:131], v38, s[14:15] offset:1024
	global_load_dwordx4 v[116:119], v38, s[12:13] offset:2048
	global_load_dwordx4 v[132:135], v38, s[14:15] offset:2048
	global_load_dwordx4 v[120:123], v38, s[12:13] offset:3072
	global_load_dwordx4 v[136:139], v38, s[14:15] offset:3072
	s_mov_b32 s16, 0x0
	v_lshl_add_u64 v[26:27], v[84:85], 0, s[16:17]
	global_load_dwordx4 v[140:143], v[26:27], off
	global_load_dwordx4 v[144:147], v[26:27], off offset:1024
	global_load_dwordx4 v[148:151], v[26:27], off offset:2048
	global_load_dwordx4 v[152:155], v[26:27], off offset:3072
	s_mov_b32 s16, 0x800000
	v_lshl_add_u64 v[26:27], v[84:85], 0, s[16:17]
	global_load_dwordx4 v[156:159], v[26:27], off
	global_load_dwordx4 v[160:163], v[26:27], off offset:1024
	global_load_dwordx4 v[164:167], v[26:27], off offset:2048
	global_load_dwordx4 v[168:171], v[26:27], off offset:3072
	s_mov_b32 s16, 0x1000000
	v_lshl_add_u64 v[26:27], v[84:85], 0, s[16:17]
	global_load_dwordx4 v[172:175], v[26:27], off
	global_load_dwordx4 v[176:179], v[26:27], off offset:1024
	global_load_dwordx4 v[180:183], v[26:27], off offset:2048
	global_load_dwordx4 v[184:187], v[26:27], off offset:3072
	s_mov_b32 s16, 0x1800000
	v_lshl_add_u64 v[26:27], v[84:85], 0, s[16:17]
	global_load_dwordx4 v[188:191], v[26:27], off
	global_load_dwordx4 v[192:195], v[26:27], off offset:1024
	global_load_dwordx4 v[196:199], v[26:27], off offset:2048
	global_load_dwordx4 v[200:203], v[26:27], off offset:3072
	s_mov_b32 s16, 0x2000000
	v_lshl_add_u64 v[26:27], v[84:85], 0, s[16:17]
	global_load_dwordx4 v[0:3], v[26:27], off
	global_load_dwordx4 v[4:7], v[26:27], off offset:1024
	global_load_dwordx4 v[8:11], v[26:27], off offset:2048
	global_load_dwordx4 v[12:15], v[26:27], off offset:3072
	s_mov_b32 s16, 0x2800000
	v_lshl_add_u64 v[26:27], v[84:85], 0, s[16:17]
	global_load_dwordx4 v[28:31], v[26:27], off
	global_load_dwordx4 v[32:35], v[26:27], off offset:1024
	global_load_dwordx4 v[44:47], v[26:27], off offset:2048
	global_load_dwordx4 v[48:51], v[26:27], off offset:3072
	s_mov_b32 s16, 0x3000000
	v_lshl_add_u64 v[26:27], v[84:85], 0, s[16:17]
	global_load_dwordx4 v[52:55], v[26:27], off
	global_load_dwordx4 v[56:59], v[26:27], off offset:1024
	global_load_dwordx4 v[60:63], v[26:27], off offset:2048
	global_load_dwordx4 v[64:67], v[26:27], off offset:3072
	s_mov_b32 s16, 0x3800000
	v_lshl_add_u64 v[26:27], v[84:85], 0, s[16:17]
	global_load_dwordx4 v[68:71], v[26:27], off
	global_load_dwordx4 v[72:75], v[26:27], off offset:1024
	global_load_dwordx4 v[76:79], v[26:27], off offset:2048
	global_load_dwordx4 v[80:83], v[26:27], off offset:3072
	s_waitcnt vmcnt(16)
	s_mov_b32 s16, 0x0
	v_lshl_add_u64 v[42:43], v[86:87], 0, s[16:17]
	v_cvt_pk_bf16_f32 v218, v140, v141
	v_cvt_pk_bf16_f32 v219, v142, v143
	global_store_dwordx2 v[42:43], v[218:219], off
	v_cvt_pk_bf16_f32 v218, v144, v145
	v_cvt_pk_bf16_f32 v219, v146, v147
	global_store_dwordx2 v[42:43], v[218:219], off offset:512
	v_cvt_pk_bf16_f32 v218, v148, v149
	v_cvt_pk_bf16_f32 v219, v150, v151
	global_store_dwordx2 v[42:43], v[218:219], off offset:1024
	v_cvt_pk_bf16_f32 v218, v152, v153
	v_cvt_pk_bf16_f32 v219, v154, v155
	global_store_dwordx2 v[42:43], v[218:219], off offset:1536
	s_mov_b32 s16, 0x400000
	v_lshl_add_u64 v[42:43], v[86:87], 0, s[16:17]
	v_cvt_pk_bf16_f32 v218, v156, v157
	v_cvt_pk_bf16_f32 v219, v158, v159
	global_store_dwordx2 v[42:43], v[218:219], off
	v_cvt_pk_bf16_f32 v218, v160, v161
	v_cvt_pk_bf16_f32 v219, v162, v163
	global_store_dwordx2 v[42:43], v[218:219], off offset:512
	v_cvt_pk_bf16_f32 v218, v164, v165
	v_cvt_pk_bf16_f32 v219, v166, v167
	global_store_dwordx2 v[42:43], v[218:219], off offset:1024
	v_cvt_pk_bf16_f32 v218, v168, v169
	v_cvt_pk_bf16_f32 v219, v170, v171
	global_store_dwordx2 v[42:43], v[218:219], off offset:1536
	s_mov_b32 s16, 0x800000
	v_lshl_add_u64 v[42:43], v[86:87], 0, s[16:17]
	v_cvt_pk_bf16_f32 v218, v172, v173
	v_cvt_pk_bf16_f32 v219, v174, v175
	global_store_dwordx2 v[42:43], v[218:219], off
	v_cvt_pk_bf16_f32 v218, v176, v177
	v_cvt_pk_bf16_f32 v219, v178, v179
	global_store_dwordx2 v[42:43], v[218:219], off offset:512
	v_cvt_pk_bf16_f32 v218, v180, v181
	v_cvt_pk_bf16_f32 v219, v182, v183
	global_store_dwordx2 v[42:43], v[218:219], off offset:1024
	v_cvt_pk_bf16_f32 v218, v184, v185
	v_cvt_pk_bf16_f32 v219, v186, v187
	global_store_dwordx2 v[42:43], v[218:219], off offset:1536
	s_mov_b32 s16, 0xc00000
	v_lshl_add_u64 v[42:43], v[86:87], 0, s[16:17]
	v_cvt_pk_bf16_f32 v218, v188, v189
	v_cvt_pk_bf16_f32 v219, v190, v191
	global_store_dwordx2 v[42:43], v[218:219], off
	v_cvt_pk_bf16_f32 v218, v192, v193
	v_cvt_pk_bf16_f32 v219, v194, v195
	global_store_dwordx2 v[42:43], v[218:219], off offset:512
	v_cvt_pk_bf16_f32 v218, v196, v197
	v_cvt_pk_bf16_f32 v219, v198, v199
	global_store_dwordx2 v[42:43], v[218:219], off offset:1024
	v_cvt_pk_bf16_f32 v218, v200, v201
	v_cvt_pk_bf16_f32 v219, v202, v203
	global_store_dwordx2 v[42:43], v[218:219], off offset:1536
	v_pk_mul_f32 v[218:219], v[140:141], v[140:141]
	v_pk_fma_f32 v[218:219], v[142:143], v[142:143], v[218:219]
	v_pk_fma_f32 v[218:219], v[144:145], v[144:145], v[218:219]
	v_pk_fma_f32 v[218:219], v[146:147], v[146:147], v[218:219]
	v_pk_fma_f32 v[218:219], v[148:149], v[148:149], v[218:219]
	v_pk_fma_f32 v[218:219], v[150:151], v[150:151], v[218:219]
	v_pk_fma_f32 v[218:219], v[152:153], v[152:153], v[218:219]
	v_pk_fma_f32 v[218:219], v[154:155], v[154:155], v[218:219]
	v_add_f32_e32 v204, v218, v219
	v_pk_mul_f32 v[218:219], v[156:157], v[156:157]
	v_pk_fma_f32 v[218:219], v[158:159], v[158:159], v[218:219]
	v_pk_fma_f32 v[218:219], v[160:161], v[160:161], v[218:219]
	v_pk_fma_f32 v[218:219], v[162:163], v[162:163], v[218:219]
	v_pk_fma_f32 v[218:219], v[164:165], v[164:165], v[218:219]
	v_pk_fma_f32 v[218:219], v[166:167], v[166:167], v[218:219]
	v_pk_fma_f32 v[218:219], v[168:169], v[168:169], v[218:219]
	v_pk_fma_f32 v[218:219], v[170:171], v[170:171], v[218:219]
	v_add_f32_e32 v206, v218, v219
	v_pk_mul_f32 v[218:219], v[172:173], v[172:173]
	v_pk_fma_f32 v[218:219], v[174:175], v[174:175], v[218:219]
	v_pk_fma_f32 v[218:219], v[176:177], v[176:177], v[218:219]
	v_pk_fma_f32 v[218:219], v[178:179], v[178:179], v[218:219]
	v_pk_fma_f32 v[218:219], v[180:181], v[180:181], v[218:219]
	v_pk_fma_f32 v[218:219], v[182:183], v[182:183], v[218:219]
	v_pk_fma_f32 v[218:219], v[184:185], v[184:185], v[218:219]
	v_pk_fma_f32 v[218:219], v[186:187], v[186:187], v[218:219]
	v_add_f32_e32 v208, v218, v219
	v_pk_mul_f32 v[218:219], v[188:189], v[188:189]
	v_pk_fma_f32 v[218:219], v[190:191], v[190:191], v[218:219]
	v_pk_fma_f32 v[218:219], v[192:193], v[192:193], v[218:219]
	v_pk_fma_f32 v[218:219], v[194:195], v[194:195], v[218:219]
	v_pk_fma_f32 v[218:219], v[196:197], v[196:197], v[218:219]
	v_pk_fma_f32 v[218:219], v[198:199], v[198:199], v[218:219]
	v_pk_fma_f32 v[218:219], v[200:201], v[200:201], v[218:219]
	v_pk_fma_f32 v[218:219], v[202:203], v[202:203], v[218:219]
	v_add_f32_e32 v210, v218, v219
	ds_bpermute_b32 v205, v212, v204
	ds_bpermute_b32 v207, v212, v206
	ds_bpermute_b32 v209, v212, v208
	ds_bpermute_b32 v211, v212, v210
	s_waitcnt lgkmcnt(0)
	v_add_f32_e32 v204, v204, v205
	v_add_f32_e32 v206, v206, v207
	v_add_f32_e32 v208, v208, v209
	v_add_f32_e32 v210, v210, v211
	ds_bpermute_b32 v205, v213, v204
	ds_bpermute_b32 v207, v213, v206
	ds_bpermute_b32 v209, v213, v208
	ds_bpermute_b32 v211, v213, v210
	s_waitcnt lgkmcnt(0)
	v_add_f32_e32 v204, v204, v205
	v_add_f32_e32 v206, v206, v207
	v_add_f32_e32 v208, v208, v209
	v_add_f32_e32 v210, v210, v211
	ds_bpermute_b32 v205, v214, v204
	ds_bpermute_b32 v207, v214, v206
	ds_bpermute_b32 v209, v214, v208
	ds_bpermute_b32 v211, v214, v210
	s_waitcnt lgkmcnt(0)
	v_add_f32_e32 v204, v204, v205
	v_add_f32_e32 v206, v206, v207
	v_add_f32_e32 v208, v208, v209
	v_add_f32_e32 v210, v210, v211
	ds_bpermute_b32 v205, v215, v204
	ds_bpermute_b32 v207, v215, v206
	ds_bpermute_b32 v209, v215, v208
	ds_bpermute_b32 v211, v215, v210
	s_waitcnt lgkmcnt(0)
	v_add_f32_e32 v204, v204, v205
	v_add_f32_e32 v206, v206, v207
	v_add_f32_e32 v208, v208, v209
	v_add_f32_e32 v210, v210, v211
	ds_bpermute_b32 v205, v216, v204
	ds_bpermute_b32 v207, v216, v206
	ds_bpermute_b32 v209, v216, v208
	ds_bpermute_b32 v211, v216, v210
	s_waitcnt lgkmcnt(0)
	v_add_f32_e32 v204, v204, v205
	v_add_f32_e32 v206, v206, v207
	v_add_f32_e32 v208, v208, v209
	v_add_f32_e32 v210, v210, v211
	ds_bpermute_b32 v205, v217, v204
	ds_bpermute_b32 v207, v217, v206
	ds_bpermute_b32 v209, v217, v208
	ds_bpermute_b32 v211, v217, v210
	s_waitcnt lgkmcnt(0)
	v_add_f32_e32 v204, v204, v205
	v_add_f32_e32 v206, v206, v207
	v_add_f32_e32 v208, v208, v209
	v_add_f32_e32 v210, v210, v211
	v_fmamk_f32 v204, v204, 0x3a800000, v37
	v_fmamk_f32 v206, v206, 0x3a800000, v37
	v_fmamk_f32 v208, v208, 0x3a800000, v37
	v_fmamk_f32 v210, v210, 0x3a800000, v37
	v_rsq_f32_e32 v204, v204
	v_rsq_f32_e32 v206, v206
	v_rsq_f32_e32 v208, v208
	v_rsq_f32_e32 v210, v210
	v_pk_add_f32 v[124:125], v[124:125], 1.0 op_sel_hi:[1,0]
	v_pk_add_f32 v[126:127], v[126:127], 1.0 op_sel_hi:[1,0]
	v_pk_add_f32 v[128:129], v[128:129], 1.0 op_sel_hi:[1,0]
	v_pk_add_f32 v[130:131], v[130:131], 1.0 op_sel_hi:[1,0]
	v_pk_add_f32 v[132:133], v[132:133], 1.0 op_sel_hi:[1,0]
	v_pk_add_f32 v[134:135], v[134:135], 1.0 op_sel_hi:[1,0]
	v_pk_add_f32 v[136:137], v[136:137], 1.0 op_sel_hi:[1,0]
	v_pk_add_f32 v[138:139], v[138:139], 1.0 op_sel_hi:[1,0]
	s_mov_b32 s16, 0x0
	v_lshl_add_u64 v[88:89], v[16:17], 0, s[16:17]
	v_pk_mul_f32 v[140:141], v[140:141], v[204:205] op_sel_hi:[1,0]
	v_pk_mul_f32 v[142:143], v[142:143], v[204:205] op_sel_hi:[1,0]
	v_pk_mul_f32 v[140:141], v[92:93], v[140:141]
	v_pk_mul_f32 v[142:143], v[94:95], v[142:143]
	v_pk_fma_f32 v[140:141], v[124:125], v[140:141], v[108:109]
	v_pk_fma_f32 v[142:143], v[126:127], v[142:143], v[110:111]
	v_cvt_pk_bf16_f32 v140, v140, v141
	v_cvt_pk_bf16_f32 v141, v142, v143
	global_store_dwordx2 v[88:89], v[140:141], off
	v_pk_mul_f32 v[144:145], v[144:145], v[204:205] op_sel_hi:[1,0]
	v_pk_mul_f32 v[146:147], v[146:147], v[204:205] op_sel_hi:[1,0]
	v_pk_mul_f32 v[144:145], v[96:97], v[144:145]
	v_pk_mul_f32 v[146:147], v[98:99], v[146:147]
	v_pk_fma_f32 v[144:145], v[128:129], v[144:145], v[112:113]
	v_pk_fma_f32 v[146:147], v[130:131], v[146:147], v[114:115]
	v_cvt_pk_bf16_f32 v144, v144, v145
	v_cvt_pk_bf16_f32 v145, v146, v147
	global_store_dwordx2 v[88:89], v[144:145], off offset:512
	v_pk_mul_f32 v[148:149], v[148:149], v[204:205] op_sel_hi:[1,0]
	v_pk_mul_f32 v[150:151], v[150:151], v[204:205] op_sel_hi:[1,0]
	v_pk_mul_f32 v[148:149], v[100:101], v[148:149]
	v_pk_mul_f32 v[150:151], v[102:103], v[150:151]
	v_pk_fma_f32 v[148:149], v[132:133], v[148:149], v[116:117]
	v_pk_fma_f32 v[150:151], v[134:135], v[150:151], v[118:119]
	v_cvt_pk_bf16_f32 v148, v148, v149
	v_cvt_pk_bf16_f32 v149, v150, v151
	global_store_dwordx2 v[88:89], v[148:149], off offset:1024
	v_pk_mul_f32 v[152:153], v[152:153], v[204:205] op_sel_hi:[1,0]
	v_pk_mul_f32 v[154:155], v[154:155], v[204:205] op_sel_hi:[1,0]
	v_pk_mul_f32 v[152:153], v[104:105], v[152:153]
	v_pk_mul_f32 v[154:155], v[106:107], v[154:155]
	v_pk_fma_f32 v[152:153], v[136:137], v[152:153], v[120:121]
	v_pk_fma_f32 v[154:155], v[138:139], v[154:155], v[122:123]
	v_cvt_pk_bf16_f32 v152, v152, v153
	v_cvt_pk_bf16_f32 v153, v154, v155
	global_store_dwordx2 v[88:89], v[152:153], off offset:1536
	s_mov_b32 s16, 0x400000
	v_lshl_add_u64 v[88:89], v[16:17], 0, s[16:17]
	v_pk_mul_f32 v[156:157], v[156:157], v[206:207] op_sel_hi:[1,0]
	v_pk_mul_f32 v[158:159], v[158:159], v[206:207] op_sel_hi:[1,0]
	v_pk_mul_f32 v[156:157], v[92:93], v[156:157]
	v_pk_mul_f32 v[158:159], v[94:95], v[158:159]
	v_pk_fma_f32 v[156:157], v[124:125], v[156:157], v[108:109]
	v_pk_fma_f32 v[158:159], v[126:127], v[158:159], v[110:111]
	v_cvt_pk_bf16_f32 v156, v156, v157
	v_cvt_pk_bf16_f32 v157, v158, v159
	global_store_dwordx2 v[88:89], v[156:157], off
	v_pk_mul_f32 v[160:161], v[160:161], v[206:207] op_sel_hi:[1,0]
	v_pk_mul_f32 v[162:163], v[162:163], v[206:207] op_sel_hi:[1,0]
	v_pk_mul_f32 v[160:161], v[96:97], v[160:161]
	v_pk_mul_f32 v[162:163], v[98:99], v[162:163]
	v_pk_fma_f32 v[160:161], v[128:129], v[160:161], v[112:113]
	v_pk_fma_f32 v[162:163], v[130:131], v[162:163], v[114:115]
	v_cvt_pk_bf16_f32 v160, v160, v161
	v_cvt_pk_bf16_f32 v161, v162, v163
	global_store_dwordx2 v[88:89], v[160:161], off offset:512
	v_pk_mul_f32 v[164:165], v[164:165], v[206:207] op_sel_hi:[1,0]
	v_pk_mul_f32 v[166:167], v[166:167], v[206:207] op_sel_hi:[1,0]
	v_pk_mul_f32 v[164:165], v[100:101], v[164:165]
	v_pk_mul_f32 v[166:167], v[102:103], v[166:167]
	v_pk_fma_f32 v[164:165], v[132:133], v[164:165], v[116:117]
	v_pk_fma_f32 v[166:167], v[134:135], v[166:167], v[118:119]
	v_cvt_pk_bf16_f32 v164, v164, v165
	v_cvt_pk_bf16_f32 v165, v166, v167
	global_store_dwordx2 v[88:89], v[164:165], off offset:1024
	v_pk_mul_f32 v[168:169], v[168:169], v[206:207] op_sel_hi:[1,0]
	v_pk_mul_f32 v[170:171], v[170:171], v[206:207] op_sel_hi:[1,0]
	v_pk_mul_f32 v[168:169], v[104:105], v[168:169]
	v_pk_mul_f32 v[170:171], v[106:107], v[170:171]
	v_pk_fma_f32 v[168:169], v[136:137], v[168:169], v[120:121]
	v_pk_fma_f32 v[170:171], v[138:139], v[170:171], v[122:123]
	v_cvt_pk_bf16_f32 v168, v168, v169
	v_cvt_pk_bf16_f32 v169, v170, v171
	global_store_dwordx2 v[88:89], v[168:169], off offset:1536
	s_mov_b32 s16, 0x800000
	v_lshl_add_u64 v[88:89], v[16:17], 0, s[16:17]
	v_pk_mul_f32 v[172:173], v[172:173], v[208:209] op_sel_hi:[1,0]
	v_pk_mul_f32 v[174:175], v[174:175], v[208:209] op_sel_hi:[1,0]
	v_pk_mul_f32 v[172:173], v[92:93], v[172:173]
	v_pk_mul_f32 v[174:175], v[94:95], v[174:175]
	v_pk_fma_f32 v[172:173], v[124:125], v[172:173], v[108:109]
	v_pk_fma_f32 v[174:175], v[126:127], v[174:175], v[110:111]
	v_cvt_pk_bf16_f32 v172, v172, v173
	v_cvt_pk_bf16_f32 v173, v174, v175
	global_store_dwordx2 v[88:89], v[172:173], off
	v_pk_mul_f32 v[176:177], v[176:177], v[208:209] op_sel_hi:[1,0]
	v_pk_mul_f32 v[178:179], v[178:179], v[208:209] op_sel_hi:[1,0]
	v_pk_mul_f32 v[176:177], v[96:97], v[176:177]
	v_pk_mul_f32 v[178:179], v[98:99], v[178:179]
	v_pk_fma_f32 v[176:177], v[128:129], v[176:177], v[112:113]
	v_pk_fma_f32 v[178:179], v[130:131], v[178:179], v[114:115]
	v_cvt_pk_bf16_f32 v176, v176, v177
	v_cvt_pk_bf16_f32 v177, v178, v179
	global_store_dwordx2 v[88:89], v[176:177], off offset:512
	v_pk_mul_f32 v[180:181], v[180:181], v[208:209] op_sel_hi:[1,0]
	v_pk_mul_f32 v[182:183], v[182:183], v[208:209] op_sel_hi:[1,0]
	v_pk_mul_f32 v[180:181], v[100:101], v[180:181]
	v_pk_mul_f32 v[182:183], v[102:103], v[182:183]
	v_pk_fma_f32 v[180:181], v[132:133], v[180:181], v[116:117]
	v_pk_fma_f32 v[182:183], v[134:135], v[182:183], v[118:119]
	v_cvt_pk_bf16_f32 v180, v180, v181
	v_cvt_pk_bf16_f32 v181, v182, v183
	global_store_dwordx2 v[88:89], v[180:181], off offset:1024
	v_pk_mul_f32 v[184:185], v[184:185], v[208:209] op_sel_hi:[1,0]
	v_pk_mul_f32 v[186:187], v[186:187], v[208:209] op_sel_hi:[1,0]
	v_pk_mul_f32 v[184:185], v[104:105], v[184:185]
	v_pk_mul_f32 v[186:187], v[106:107], v[186:187]
	v_pk_fma_f32 v[184:185], v[136:137], v[184:185], v[120:121]
	v_pk_fma_f32 v[186:187], v[138:139], v[186:187], v[122:123]
	v_cvt_pk_bf16_f32 v184, v184, v185
	v_cvt_pk_bf16_f32 v185, v186, v187
	global_store_dwordx2 v[88:89], v[184:185], off offset:1536
	s_mov_b32 s16, 0xc00000
	v_lshl_add_u64 v[88:89], v[16:17], 0, s[16:17]
	v_pk_mul_f32 v[188:189], v[188:189], v[210:211] op_sel_hi:[1,0]
	v_pk_mul_f32 v[190:191], v[190:191], v[210:211] op_sel_hi:[1,0]
	v_pk_mul_f32 v[188:189], v[92:93], v[188:189]
	v_pk_mul_f32 v[190:191], v[94:95], v[190:191]
	v_pk_fma_f32 v[188:189], v[124:125], v[188:189], v[108:109]
	v_pk_fma_f32 v[190:191], v[126:127], v[190:191], v[110:111]
	v_cvt_pk_bf16_f32 v188, v188, v189
	v_cvt_pk_bf16_f32 v189, v190, v191
	global_store_dwordx2 v[88:89], v[188:189], off
	v_pk_mul_f32 v[192:193], v[192:193], v[210:211] op_sel_hi:[1,0]
	v_pk_mul_f32 v[194:195], v[194:195], v[210:211] op_sel_hi:[1,0]
	v_pk_mul_f32 v[192:193], v[96:97], v[192:193]
	v_pk_mul_f32 v[194:195], v[98:99], v[194:195]
	v_pk_fma_f32 v[192:193], v[128:129], v[192:193], v[112:113]
	v_pk_fma_f32 v[194:195], v[130:131], v[194:195], v[114:115]
	v_cvt_pk_bf16_f32 v192, v192, v193
	v_cvt_pk_bf16_f32 v193, v194, v195
	global_store_dwordx2 v[88:89], v[192:193], off offset:512
	v_pk_mul_f32 v[196:197], v[196:197], v[210:211] op_sel_hi:[1,0]
	v_pk_mul_f32 v[198:199], v[198:199], v[210:211] op_sel_hi:[1,0]
	v_pk_mul_f32 v[196:197], v[100:101], v[196:197]
	v_pk_mul_f32 v[198:199], v[102:103], v[198:199]
	v_pk_fma_f32 v[196:197], v[132:133], v[196:197], v[116:117]
	v_pk_fma_f32 v[198:199], v[134:135], v[198:199], v[118:119]
	v_cvt_pk_bf16_f32 v196, v196, v197
	v_cvt_pk_bf16_f32 v197, v198, v199
	global_store_dwordx2 v[88:89], v[196:197], off offset:1024
	v_pk_mul_f32 v[200:201], v[200:201], v[210:211] op_sel_hi:[1,0]
	v_pk_mul_f32 v[202:203], v[202:203], v[210:211] op_sel_hi:[1,0]
	v_pk_mul_f32 v[200:201], v[104:105], v[200:201]
	v_pk_mul_f32 v[202:203], v[106:107], v[202:203]
	v_pk_fma_f32 v[200:201], v[136:137], v[200:201], v[120:121]
	v_pk_fma_f32 v[202:203], v[138:139], v[202:203], v[122:123]
	v_cvt_pk_bf16_f32 v200, v200, v201
	v_cvt_pk_bf16_f32 v201, v202, v203
	global_store_dwordx2 v[88:89], v[200:201], off offset:1536
	s_add_u32 s12, s4, 0x6000
	s_addc_u32 s13, s5, 0
	s_add_u32 s14, s12, 0x1000
	s_addc_u32 s15, s13, 0
	global_load_dwordx4 v[108:111], v38, s[12:13]
	global_load_dwordx4 v[124:127], v38, s[14:15]
	global_load_dwordx4 v[112:115], v38, s[12:13] offset:1024
	global_load_dwordx4 v[128:131], v38, s[14:15] offset:1024
	global_load_dwordx4 v[116:119], v38, s[12:13] offset:2048
	global_load_dwordx4 v[132:135], v38, s[14:15] offset:2048
	global_load_dwordx4 v[120:123], v38, s[12:13] offset:3072
	global_load_dwordx4 v[136:139], v38, s[14:15] offset:3072
	s_cmpk_gt_u32 s0, 0x1ff
	s_cbranch_scc1 .La0_noctx_pf
	s_lshl_b32 s16, s0, 12
	v_lshl_add_u64 v[26:27], v[20:21], 0, s[16:17]
	global_load_dwordx4 v[140:143], v[26:27], off
	global_load_dwordx4 v[144:147], v[26:27], off offset:1024
	global_load_dwordx4 v[148:151], v[26:27], off offset:2048
	global_load_dwordx4 v[152:155], v[26:27], off offset:3072
.La0_noctx_pf:
	s_waitcnt vmcnt(0)
	s_mov_b32 s16, 0x1000000
	v_lshl_add_u64 v[42:43], v[86:87], 0, s[16:17]
	v_cvt_pk_bf16_f32 v218, v0, v1
	v_cvt_pk_bf16_f32 v219, v2, v3
	global_store_dwordx2 v[42:43], v[218:219], off
	v_cvt_pk_bf16_f32 v218, v4, v5
	v_cvt_pk_bf16_f32 v219, v6, v7
	global_store_dwordx2 v[42:43], v[218:219], off offset:512
	v_cvt_pk_bf16_f32 v218, v8, v9
	v_cvt_pk_bf16_f32 v219, v10, v11
	global_store_dwordx2 v[42:43], v[218:219], off offset:1024
	v_cvt_pk_bf16_f32 v218, v12, v13
	v_cvt_pk_bf16_f32 v219, v14, v15
	global_store_dwordx2 v[42:43], v[218:219], off offset:1536
	s_mov_b32 s16, 0x1400000
	v_lshl_add_u64 v[42:43], v[86:87], 0, s[16:17]
	v_cvt_pk_bf16_f32 v218, v28, v29
	v_cvt_pk_bf16_f32 v219, v30, v31
	global_store_dwordx2 v[42:43], v[218:219], off
	v_cvt_pk_bf16_f32 v218, v32, v33
	v_cvt_pk_bf16_f32 v219, v34, v35
	global_store_dwordx2 v[42:43], v[218:219], off offset:512
	v_cvt_pk_bf16_f32 v218, v44, v45
	v_cvt_pk_bf16_f32 v219, v46, v47
	global_store_dwordx2 v[42:43], v[218:219], off offset:1024
	v_cvt_pk_bf16_f32 v218, v48, v49
	v_cvt_pk_bf16_f32 v219, v50, v51
	global_store_dwordx2 v[42:43], v[218:219], off offset:1536
	s_mov_b32 s16, 0x1800000
	v_lshl_add_u64 v[42:43], v[86:87], 0, s[16:17]
	v_cvt_pk_bf16_f32 v218, v52, v53
	v_cvt_pk_bf16_f32 v219, v54, v55
	global_store_dwordx2 v[42:43], v[218:219], off
	v_cvt_pk_bf16_f32 v218, v56, v57
	v_cvt_pk_bf16_f32 v219, v58, v59
	global_store_dwordx2 v[42:43], v[218:219], off offset:512
	v_cvt_pk_bf16_f32 v218, v60, v61
	v_cvt_pk_bf16_f32 v219, v62, v63
	global_store_dwordx2 v[42:43], v[218:219], off offset:1024
	v_cvt_pk_bf16_f32 v218, v64, v65
	v_cvt_pk_bf16_f32 v219, v66, v67
	global_store_dwordx2 v[42:43], v[218:219], off offset:1536
	s_mov_b32 s16, 0x1c00000
	v_lshl_add_u64 v[42:43], v[86:87], 0, s[16:17]
	v_cvt_pk_bf16_f32 v218, v68, v69
	v_cvt_pk_bf16_f32 v219, v70, v71
	global_store_dwordx2 v[42:43], v[218:219], off
	v_cvt_pk_bf16_f32 v218, v72, v73
	v_cvt_pk_bf16_f32 v219, v74, v75
	global_store_dwordx2 v[42:43], v[218:219], off offset:512
	v_cvt_pk_bf16_f32 v218, v76, v77
	v_cvt_pk_bf16_f32 v219, v78, v79
	global_store_dwordx2 v[42:43], v[218:219], off offset:1024
	v_cvt_pk_bf16_f32 v218, v80, v81
	v_cvt_pk_bf16_f32 v219, v82, v83
	global_store_dwordx2 v[42:43], v[218:219], off offset:1536
	v_pk_mul_f32 v[218:219], v[0:1], v[0:1]
	v_pk_fma_f32 v[218:219], v[2:3], v[2:3], v[218:219]
	v_pk_fma_f32 v[218:219], v[4:5], v[4:5], v[218:219]
	v_pk_fma_f32 v[218:219], v[6:7], v[6:7], v[218:219]
	v_pk_fma_f32 v[218:219], v[8:9], v[8:9], v[218:219]
	v_pk_fma_f32 v[218:219], v[10:11], v[10:11], v[218:219]
	v_pk_fma_f32 v[218:219], v[12:13], v[12:13], v[218:219]
	v_pk_fma_f32 v[218:219], v[14:15], v[14:15], v[218:219]
	v_add_f32_e32 v204, v218, v219
	v_pk_mul_f32 v[218:219], v[28:29], v[28:29]
	v_pk_fma_f32 v[218:219], v[30:31], v[30:31], v[218:219]
	v_pk_fma_f32 v[218:219], v[32:33], v[32:33], v[218:219]
	v_pk_fma_f32 v[218:219], v[34:35], v[34:35], v[218:219]
	v_pk_fma_f32 v[218:219], v[44:45], v[44:45], v[218:219]
	v_pk_fma_f32 v[218:219], v[46:47], v[46:47], v[218:219]
	v_pk_fma_f32 v[218:219], v[48:49], v[48:49], v[218:219]
	v_pk_fma_f32 v[218:219], v[50:51], v[50:51], v[218:219]
	v_add_f32_e32 v206, v218, v219
	v_pk_mul_f32 v[218:219], v[52:53], v[52:53]
	v_pk_fma_f32 v[218:219], v[54:55], v[54:55], v[218:219]
	v_pk_fma_f32 v[218:219], v[56:57], v[56:57], v[218:219]
	v_pk_fma_f32 v[218:219], v[58:59], v[58:59], v[218:219]
	v_pk_fma_f32 v[218:219], v[60:61], v[60:61], v[218:219]
	v_pk_fma_f32 v[218:219], v[62:63], v[62:63], v[218:219]
	v_pk_fma_f32 v[218:219], v[64:65], v[64:65], v[218:219]
	v_pk_fma_f32 v[218:219], v[66:67], v[66:67], v[218:219]
	v_add_f32_e32 v208, v218, v219
	v_pk_mul_f32 v[218:219], v[68:69], v[68:69]
	v_pk_fma_f32 v[218:219], v[70:71], v[70:71], v[218:219]
	v_pk_fma_f32 v[218:219], v[72:73], v[72:73], v[218:219]
	v_pk_fma_f32 v[218:219], v[74:75], v[74:75], v[218:219]
	v_pk_fma_f32 v[218:219], v[76:77], v[76:77], v[218:219]
	v_pk_fma_f32 v[218:219], v[78:79], v[78:79], v[218:219]
	v_pk_fma_f32 v[218:219], v[80:81], v[80:81], v[218:219]
	v_pk_fma_f32 v[218:219], v[82:83], v[82:83], v[218:219]
	v_add_f32_e32 v210, v218, v219
	ds_bpermute_b32 v205, v212, v204
	ds_bpermute_b32 v207, v212, v206
	ds_bpermute_b32 v209, v212, v208
	ds_bpermute_b32 v211, v212, v210
	s_waitcnt lgkmcnt(0)
	v_add_f32_e32 v204, v204, v205
	v_add_f32_e32 v206, v206, v207
	v_add_f32_e32 v208, v208, v209
	v_add_f32_e32 v210, v210, v211
	ds_bpermute_b32 v205, v213, v204
	ds_bpermute_b32 v207, v213, v206
	ds_bpermute_b32 v209, v213, v208
	ds_bpermute_b32 v211, v213, v210
	s_waitcnt lgkmcnt(0)
	v_add_f32_e32 v204, v204, v205
	v_add_f32_e32 v206, v206, v207
	v_add_f32_e32 v208, v208, v209
	v_add_f32_e32 v210, v210, v211
	ds_bpermute_b32 v205, v214, v204
	ds_bpermute_b32 v207, v214, v206
	ds_bpermute_b32 v209, v214, v208
	ds_bpermute_b32 v211, v214, v210
	s_waitcnt lgkmcnt(0)
	v_add_f32_e32 v204, v204, v205
	v_add_f32_e32 v206, v206, v207
	v_add_f32_e32 v208, v208, v209
	v_add_f32_e32 v210, v210, v211
	ds_bpermute_b32 v205, v215, v204
	ds_bpermute_b32 v207, v215, v206
	ds_bpermute_b32 v209, v215, v208
	ds_bpermute_b32 v211, v215, v210
	s_waitcnt lgkmcnt(0)
	v_add_f32_e32 v204, v204, v205
	v_add_f32_e32 v206, v206, v207
	v_add_f32_e32 v208, v208, v209
	v_add_f32_e32 v210, v210, v211
	ds_bpermute_b32 v205, v216, v204
	ds_bpermute_b32 v207, v216, v206
	ds_bpermute_b32 v209, v216, v208
	ds_bpermute_b32 v211, v216, v210
	s_waitcnt lgkmcnt(0)
	v_add_f32_e32 v204, v204, v205
	v_add_f32_e32 v206, v206, v207
	v_add_f32_e32 v208, v208, v209
	v_add_f32_e32 v210, v210, v211
	ds_bpermute_b32 v205, v217, v204
	ds_bpermute_b32 v207, v217, v206
	ds_bpermute_b32 v209, v217, v208
	ds_bpermute_b32 v211, v217, v210
	s_waitcnt lgkmcnt(0)
	v_add_f32_e32 v204, v204, v205
	v_add_f32_e32 v206, v206, v207
	v_add_f32_e32 v208, v208, v209
	v_add_f32_e32 v210, v210, v211
	v_fmamk_f32 v204, v204, 0x3a800000, v37
	v_fmamk_f32 v206, v206, 0x3a800000, v37
	v_fmamk_f32 v208, v208, 0x3a800000, v37
	v_fmamk_f32 v210, v210, 0x3a800000, v37
	v_rsq_f32_e32 v204, v204
	v_rsq_f32_e32 v206, v206
	v_rsq_f32_e32 v208, v208
	v_rsq_f32_e32 v210, v210
	v_pk_add_f32 v[124:125], v[124:125], 1.0 op_sel_hi:[1,0]
	v_pk_add_f32 v[126:127], v[126:127], 1.0 op_sel_hi:[1,0]
	v_pk_add_f32 v[128:129], v[128:129], 1.0 op_sel_hi:[1,0]
	v_pk_add_f32 v[130:131], v[130:131], 1.0 op_sel_hi:[1,0]
	v_pk_add_f32 v[132:133], v[132:133], 1.0 op_sel_hi:[1,0]
	v_pk_add_f32 v[134:135], v[134:135], 1.0 op_sel_hi:[1,0]
	v_pk_add_f32 v[136:137], v[136:137], 1.0 op_sel_hi:[1,0]
	v_pk_add_f32 v[138:139], v[138:139], 1.0 op_sel_hi:[1,0]
	s_mov_b32 s16, 0x1000000
	v_lshl_add_u64 v[88:89], v[16:17], 0, s[16:17]
	v_pk_mul_f32 v[0:1], v[0:1], v[204:205] op_sel_hi:[1,0]
	v_pk_mul_f32 v[2:3], v[2:3], v[204:205] op_sel_hi:[1,0]
	v_pk_mul_f32 v[0:1], v[92:93], v[0:1]
	v_pk_mul_f32 v[2:3], v[94:95], v[2:3]
	v_pk_fma_f32 v[0:1], v[124:125], v[0:1], v[108:109]
	v_pk_fma_f32 v[2:3], v[126:127], v[2:3], v[110:111]
	v_cvt_pk_bf16_f32 v0, v0, v1
	v_cvt_pk_bf16_f32 v1, v2, v3
	global_store_dwordx2 v[88:89], v[0:1], off
	v_pk_mul_f32 v[4:5], v[4:5], v[204:205] op_sel_hi:[1,0]
	v_pk_mul_f32 v[6:7], v[6:7], v[204:205] op_sel_hi:[1,0]
	v_pk_mul_f32 v[4:5], v[96:97], v[4:5]
	v_pk_mul_f32 v[6:7], v[98:99], v[6:7]
	v_pk_fma_f32 v[4:5], v[128:129], v[4:5], v[112:113]
	v_pk_fma_f32 v[6:7], v[130:131], v[6:7], v[114:115]
	v_cvt_pk_bf16_f32 v4, v4, v5
	v_cvt_pk_bf16_f32 v5, v6, v7
	global_store_dwordx2 v[88:89], v[4:5], off offset:512
	v_pk_mul_f32 v[8:9], v[8:9], v[204:205] op_sel_hi:[1,0]
	v_pk_mul_f32 v[10:11], v[10:11], v[204:205] op_sel_hi:[1,0]
	v_pk_mul_f32 v[8:9], v[100:101], v[8:9]
	v_pk_mul_f32 v[10:11], v[102:103], v[10:11]
	v_pk_fma_f32 v[8:9], v[132:133], v[8:9], v[116:117]
	v_pk_fma_f32 v[10:11], v[134:135], v[10:11], v[118:119]
	v_cvt_pk_bf16_f32 v8, v8, v9
	v_cvt_pk_bf16_f32 v9, v10, v11
	global_store_dwordx2 v[88:89], v[8:9], off offset:1024
	v_pk_mul_f32 v[12:13], v[12:13], v[204:205] op_sel_hi:[1,0]
	v_pk_mul_f32 v[14:15], v[14:15], v[204:205] op_sel_hi:[1,0]
	v_pk_mul_f32 v[12:13], v[104:105], v[12:13]
	v_pk_mul_f32 v[14:15], v[106:107], v[14:15]
	v_pk_fma_f32 v[12:13], v[136:137], v[12:13], v[120:121]
	v_pk_fma_f32 v[14:15], v[138:139], v[14:15], v[122:123]
	v_cvt_pk_bf16_f32 v12, v12, v13
	v_cvt_pk_bf16_f32 v13, v14, v15
	global_store_dwordx2 v[88:89], v[12:13], off offset:1536
	s_mov_b32 s16, 0x1400000
	v_lshl_add_u64 v[88:89], v[16:17], 0, s[16:17]
	v_pk_mul_f32 v[28:29], v[28:29], v[206:207] op_sel_hi:[1,0]
	v_pk_mul_f32 v[30:31], v[30:31], v[206:207] op_sel_hi:[1,0]
	v_pk_mul_f32 v[28:29], v[92:93], v[28:29]
	v_pk_mul_f32 v[30:31], v[94:95], v[30:31]
	v_pk_fma_f32 v[28:29], v[124:125], v[28:29], v[108:109]
	v_pk_fma_f32 v[30:31], v[126:127], v[30:31], v[110:111]
	v_cvt_pk_bf16_f32 v28, v28, v29
	v_cvt_pk_bf16_f32 v29, v30, v31
	global_store_dwordx2 v[88:89], v[28:29], off
	v_pk_mul_f32 v[32:33], v[32:33], v[206:207] op_sel_hi:[1,0]
	v_pk_mul_f32 v[34:35], v[34:35], v[206:207] op_sel_hi:[1,0]
	v_pk_mul_f32 v[32:33], v[96:97], v[32:33]
	v_pk_mul_f32 v[34:35], v[98:99], v[34:35]
	v_pk_fma_f32 v[32:33], v[128:129], v[32:33], v[112:113]
	v_pk_fma_f32 v[34:35], v[130:131], v[34:35], v[114:115]
	v_cvt_pk_bf16_f32 v32, v32, v33
	v_cvt_pk_bf16_f32 v33, v34, v35
	global_store_dwordx2 v[88:89], v[32:33], off offset:512
	v_pk_mul_f32 v[44:45], v[44:45], v[206:207] op_sel_hi:[1,0]
	v_pk_mul_f32 v[46:47], v[46:47], v[206:207] op_sel_hi:[1,0]
	v_pk_mul_f32 v[44:45], v[100:101], v[44:45]
	v_pk_mul_f32 v[46:47], v[102:103], v[46:47]
	v_pk_fma_f32 v[44:45], v[132:133], v[44:45], v[116:117]
	v_pk_fma_f32 v[46:47], v[134:135], v[46:47], v[118:119]
	v_cvt_pk_bf16_f32 v44, v44, v45
	v_cvt_pk_bf16_f32 v45, v46, v47
	global_store_dwordx2 v[88:89], v[44:45], off offset:1024
	v_pk_mul_f32 v[48:49], v[48:49], v[206:207] op_sel_hi:[1,0]
	v_pk_mul_f32 v[50:51], v[50:51], v[206:207] op_sel_hi:[1,0]
	v_pk_mul_f32 v[48:49], v[104:105], v[48:49]
	v_pk_mul_f32 v[50:51], v[106:107], v[50:51]
	v_pk_fma_f32 v[48:49], v[136:137], v[48:49], v[120:121]
	v_pk_fma_f32 v[50:51], v[138:139], v[50:51], v[122:123]
	v_cvt_pk_bf16_f32 v48, v48, v49
	v_cvt_pk_bf16_f32 v49, v50, v51
	global_store_dwordx2 v[88:89], v[48:49], off offset:1536
	s_mov_b32 s16, 0x1800000
	v_lshl_add_u64 v[88:89], v[16:17], 0, s[16:17]
	v_pk_mul_f32 v[52:53], v[52:53], v[208:209] op_sel_hi:[1,0]
	v_pk_mul_f32 v[54:55], v[54:55], v[208:209] op_sel_hi:[1,0]
	v_pk_mul_f32 v[52:53], v[92:93], v[52:53]
	v_pk_mul_f32 v[54:55], v[94:95], v[54:55]
	v_pk_fma_f32 v[52:53], v[124:125], v[52:53], v[108:109]
	v_pk_fma_f32 v[54:55], v[126:127], v[54:55], v[110:111]
	v_cvt_pk_bf16_f32 v52, v52, v53
	v_cvt_pk_bf16_f32 v53, v54, v55
	global_store_dwordx2 v[88:89], v[52:53], off
	v_pk_mul_f32 v[56:57], v[56:57], v[208:209] op_sel_hi:[1,0]
	v_pk_mul_f32 v[58:59], v[58:59], v[208:209] op_sel_hi:[1,0]
	v_pk_mul_f32 v[56:57], v[96:97], v[56:57]
	v_pk_mul_f32 v[58:59], v[98:99], v[58:59]
	v_pk_fma_f32 v[56:57], v[128:129], v[56:57], v[112:113]
	v_pk_fma_f32 v[58:59], v[130:131], v[58:59], v[114:115]
	v_cvt_pk_bf16_f32 v56, v56, v57
	v_cvt_pk_bf16_f32 v57, v58, v59
	global_store_dwordx2 v[88:89], v[56:57], off offset:512
	v_pk_mul_f32 v[60:61], v[60:61], v[208:209] op_sel_hi:[1,0]
	v_pk_mul_f32 v[62:63], v[62:63], v[208:209] op_sel_hi:[1,0]
	v_pk_mul_f32 v[60:61], v[100:101], v[60:61]
	v_pk_mul_f32 v[62:63], v[102:103], v[62:63]
	v_pk_fma_f32 v[60:61], v[132:133], v[60:61], v[116:117]
	v_pk_fma_f32 v[62:63], v[134:135], v[62:63], v[118:119]
	v_cvt_pk_bf16_f32 v60, v60, v61
	v_cvt_pk_bf16_f32 v61, v62, v63
	global_store_dwordx2 v[88:89], v[60:61], off offset:1024
	v_pk_mul_f32 v[64:65], v[64:65], v[208:209] op_sel_hi:[1,0]
	v_pk_mul_f32 v[66:67], v[66:67], v[208:209] op_sel_hi:[1,0]
	v_pk_mul_f32 v[64:65], v[104:105], v[64:65]
	v_pk_mul_f32 v[66:67], v[106:107], v[66:67]
	v_pk_fma_f32 v[64:65], v[136:137], v[64:65], v[120:121]
	v_pk_fma_f32 v[66:67], v[138:139], v[66:67], v[122:123]
	v_cvt_pk_bf16_f32 v64, v64, v65
	v_cvt_pk_bf16_f32 v65, v66, v67
	global_store_dwordx2 v[88:89], v[64:65], off offset:1536
	s_mov_b32 s16, 0x1c00000
	v_lshl_add_u64 v[88:89], v[16:17], 0, s[16:17]
	v_pk_mul_f32 v[68:69], v[68:69], v[210:211] op_sel_hi:[1,0]
	v_pk_mul_f32 v[70:71], v[70:71], v[210:211] op_sel_hi:[1,0]
	v_pk_mul_f32 v[68:69], v[92:93], v[68:69]
	v_pk_mul_f32 v[70:71], v[94:95], v[70:71]
	v_pk_fma_f32 v[68:69], v[124:125], v[68:69], v[108:109]
	v_pk_fma_f32 v[70:71], v[126:127], v[70:71], v[110:111]
	v_cvt_pk_bf16_f32 v68, v68, v69
	v_cvt_pk_bf16_f32 v69, v70, v71
	global_store_dwordx2 v[88:89], v[68:69], off
	v_pk_mul_f32 v[72:73], v[72:73], v[210:211] op_sel_hi:[1,0]
	v_pk_mul_f32 v[74:75], v[74:75], v[210:211] op_sel_hi:[1,0]
	v_pk_mul_f32 v[72:73], v[96:97], v[72:73]
	v_pk_mul_f32 v[74:75], v[98:99], v[74:75]
	v_pk_fma_f32 v[72:73], v[128:129], v[72:73], v[112:113]
	v_pk_fma_f32 v[74:75], v[130:131], v[74:75], v[114:115]
	v_cvt_pk_bf16_f32 v72, v72, v73
	v_cvt_pk_bf16_f32 v73, v74, v75
	global_store_dwordx2 v[88:89], v[72:73], off offset:512
	v_pk_mul_f32 v[76:77], v[76:77], v[210:211] op_sel_hi:[1,0]
	v_pk_mul_f32 v[78:79], v[78:79], v[210:211] op_sel_hi:[1,0]
	v_pk_mul_f32 v[76:77], v[100:101], v[76:77]
	v_pk_mul_f32 v[78:79], v[102:103], v[78:79]
	v_pk_fma_f32 v[76:77], v[132:133], v[76:77], v[116:117]
	v_pk_fma_f32 v[78:79], v[134:135], v[78:79], v[118:119]
	v_cvt_pk_bf16_f32 v76, v76, v77
	v_cvt_pk_bf16_f32 v77, v78, v79
	global_store_dwordx2 v[88:89], v[76:77], off offset:1024
	v_pk_mul_f32 v[80:81], v[80:81], v[210:211] op_sel_hi:[1,0]
	v_pk_mul_f32 v[82:83], v[82:83], v[210:211] op_sel_hi:[1,0]
	v_pk_mul_f32 v[80:81], v[104:105], v[80:81]
	v_pk_mul_f32 v[82:83], v[106:107], v[82:83]
	v_pk_fma_f32 v[80:81], v[136:137], v[80:81], v[120:121]
	v_pk_fma_f32 v[82:83], v[138:139], v[82:83], v[122:123]
	v_cvt_pk_bf16_f32 v80, v80, v81
	v_cvt_pk_bf16_f32 v81, v82, v83
	global_store_dwordx2 v[88:89], v[80:81], off offset:1536
	s_cmpk_gt_u32 s0, 0x1ff
	s_cbranch_scc1 .LBB0_160
	s_add_u32 s12, s4, 0xc000
	s_addc_u32 s13, s5, 0
	s_add_u32 s14, s12, 0x1000
	s_addc_u32 s15, s13, 0
	global_load_dwordx4 v[108:111], v38, s[12:13]
	global_load_dwordx4 v[124:127], v38, s[14:15]
	global_load_dwordx4 v[112:115], v38, s[12:13] offset:1024
	global_load_dwordx4 v[128:131], v38, s[14:15] offset:1024
	global_load_dwordx4 v[116:119], v38, s[12:13] offset:2048
	global_load_dwordx4 v[132:135], v38, s[14:15] offset:2048
	global_load_dwordx4 v[120:123], v38, s[12:13] offset:3072
	global_load_dwordx4 v[136:139], v38, s[14:15] offset:3072
	s_waitcnt vmcnt(0)
	v_pk_mul_f32 v[218:219], v[140:141], v[140:141]
	v_pk_fma_f32 v[218:219], v[142:143], v[142:143], v[218:219]
	v_pk_fma_f32 v[218:219], v[144:145], v[144:145], v[218:219]
	v_pk_fma_f32 v[218:219], v[146:147], v[146:147], v[218:219]
	v_pk_fma_f32 v[218:219], v[148:149], v[148:149], v[218:219]
	v_pk_fma_f32 v[218:219], v[150:151], v[150:151], v[218:219]
	v_pk_fma_f32 v[218:219], v[152:153], v[152:153], v[218:219]
	v_pk_fma_f32 v[218:219], v[154:155], v[154:155], v[218:219]
	v_add_f32_e32 v204, v218, v219
	ds_bpermute_b32 v205, v212, v204
	s_waitcnt lgkmcnt(0)
	v_add_f32_e32 v204, v204, v205
	ds_bpermute_b32 v205, v213, v204
	s_waitcnt lgkmcnt(0)
	v_add_f32_e32 v204, v204, v205
	ds_bpermute_b32 v205, v214, v204
	s_waitcnt lgkmcnt(0)
	v_add_f32_e32 v204, v204, v205
	ds_bpermute_b32 v205, v215, v204
	s_waitcnt lgkmcnt(0)
	v_add_f32_e32 v204, v204, v205
	ds_bpermute_b32 v205, v216, v204
	s_waitcnt lgkmcnt(0)
	v_add_f32_e32 v204, v204, v205
	ds_bpermute_b32 v205, v217, v204
	s_waitcnt lgkmcnt(0)
	v_add_f32_e32 v204, v204, v205
	v_fmamk_f32 v204, v204, 0x3a800000, v37
	v_rsq_f32_e32 v204, v204
	v_pk_add_f32 v[124:125], v[124:125], 1.0 op_sel_hi:[1,0]
	v_pk_add_f32 v[126:127], v[126:127], 1.0 op_sel_hi:[1,0]
	v_pk_add_f32 v[128:129], v[128:129], 1.0 op_sel_hi:[1,0]
	v_pk_add_f32 v[130:131], v[130:131], 1.0 op_sel_hi:[1,0]
	v_pk_add_f32 v[132:133], v[132:133], 1.0 op_sel_hi:[1,0]
	v_pk_add_f32 v[134:135], v[134:135], 1.0 op_sel_hi:[1,0]
	v_pk_add_f32 v[136:137], v[136:137], 1.0 op_sel_hi:[1,0]
	v_pk_add_f32 v[138:139], v[138:139], 1.0 op_sel_hi:[1,0]
	s_mov_b32 s16, 0x2000000
	v_lshl_add_u64 v[88:89], v[16:17], 0, s[16:17]
	v_pk_mul_f32 v[140:141], v[140:141], v[204:205] op_sel_hi:[1,0]
	v_pk_mul_f32 v[142:143], v[142:143], v[204:205] op_sel_hi:[1,0]
	v_pk_mul_f32 v[140:141], v[92:93], v[140:141]
	v_pk_mul_f32 v[142:143], v[94:95], v[142:143]
	v_pk_fma_f32 v[140:141], v[124:125], v[140:141], v[108:109]
	v_pk_fma_f32 v[142:143], v[126:127], v[142:143], v[110:111]
	v_cvt_pk_bf16_f32 v140, v140, v141
	v_cvt_pk_bf16_f32 v141, v142, v143
	global_store_dwordx2 v[88:89], v[140:141], off
	v_pk_mul_f32 v[144:145], v[144:145], v[204:205] op_sel_hi:[1,0]
	v_pk_mul_f32 v[146:147], v[146:147], v[204:205] op_sel_hi:[1,0]
	v_pk_mul_f32 v[144:145], v[96:97], v[144:145]
	v_pk_mul_f32 v[146:147], v[98:99], v[146:147]
	v_pk_fma_f32 v[144:145], v[128:129], v[144:145], v[112:113]
	v_pk_fma_f32 v[146:147], v[130:131], v[146:147], v[114:115]
	v_cvt_pk_bf16_f32 v144, v144, v145
	v_cvt_pk_bf16_f32 v145, v146, v147
	global_store_dwordx2 v[88:89], v[144:145], off offset:512
	v_pk_mul_f32 v[148:149], v[148:149], v[204:205] op_sel_hi:[1,0]
	v_pk_mul_f32 v[150:151], v[150:151], v[204:205] op_sel_hi:[1,0]
	v_pk_mul_f32 v[148:149], v[100:101], v[148:149]
	v_pk_mul_f32 v[150:151], v[102:103], v[150:151]
	v_pk_fma_f32 v[148:149], v[132:133], v[148:149], v[116:117]
	v_pk_fma_f32 v[150:151], v[134:135], v[150:151], v[118:119]
	v_cvt_pk_bf16_f32 v148, v148, v149
	v_cvt_pk_bf16_f32 v149, v150, v151
	global_store_dwordx2 v[88:89], v[148:149], off offset:1024
	v_pk_mul_f32 v[152:153], v[152:153], v[204:205] op_sel_hi:[1,0]
	v_pk_mul_f32 v[154:155], v[154:155], v[204:205] op_sel_hi:[1,0]
	v_pk_mul_f32 v[152:153], v[104:105], v[152:153]
	v_pk_mul_f32 v[154:155], v[106:107], v[154:155]
	v_pk_fma_f32 v[152:153], v[136:137], v[152:153], v[120:121]
	v_pk_fma_f32 v[154:155], v[138:139], v[154:155], v[122:123]
	v_cvt_pk_bf16_f32 v152, v152, v153
	v_cvt_pk_bf16_f32 v153, v154, v155
	global_store_dwordx2 v[88:89], v[152:153], off offset:1536
	s_branch .LBB0_160
